# v26 + isel: last key tile runs an MFMA block without look-ahead key-fragment loads (no useless loads to wait for before top-k)
# baseline (speedup 1.0000x reference)
.LBB0_333:
	s_add_i32 s1, s1, 8
	s_cmp_gt_i32 s1, s34
	s_cselect_b64 s[2:3], -1, 0
	s_and_b64 vcc, exec, s[2:3]
	s_cbranch_vccnz .Lisel_lasttile
	s_waitcnt vmcnt(3)
	v_mfma_f32_32x32x16_bf16 v[50:65], v[84:87], v[148:151], 0
	v_mfma_f32_32x32x16_bf16 v[34:49], v[100:103], v[148:151], 0
	v_mfma_f32_32x32x16_bf16 v[18:33], v[116:119], v[148:151], 0
	v_mfma_f32_32x32x16_bf16 v[2:17], v[132:135], v[148:151], 0
	global_load_dwordx4 v[148:151], v[210:211], off offset:-2048
	s_waitcnt vmcnt(3)
	v_mfma_f32_32x32x16_bf16 v[50:65], v[88:91], v[152:155], v[50:65]
	v_mfma_f32_32x32x16_bf16 v[34:49], v[104:107], v[152:155], v[34:49]
	v_mfma_f32_32x32x16_bf16 v[18:33], v[120:123], v[152:155], v[18:33]
	v_mfma_f32_32x32x16_bf16 v[2:17], v[136:139], v[152:155], v[2:17]
	global_load_dwordx4 v[152:155], v[210:211], off offset:-1024
	s_waitcnt vmcnt(3)
	v_mfma_f32_32x32x16_bf16 v[50:65], v[92:95], v[156:159], v[50:65]
	v_mfma_f32_32x32x16_bf16 v[34:49], v[108:111], v[156:159], v[34:49]
	v_mfma_f32_32x32x16_bf16 v[18:33], v[124:127], v[156:159], v[18:33]
	v_mfma_f32_32x32x16_bf16 v[2:17], v[140:143], v[156:159], v[2:17]
	global_load_dwordx4 v[156:159], v[210:211], off
	s_waitcnt vmcnt(3)
	v_mfma_f32_32x32x16_bf16 v[50:65], v[96:99], v[160:163], v[50:65]
	v_mfma_f32_32x32x16_bf16 v[34:49], v[112:115], v[160:163], v[34:49]
	v_mfma_f32_32x32x16_bf16 v[18:33], v[128:131], v[160:163], v[18:33]
	v_mfma_f32_32x32x16_bf16 v[2:17], v[144:147], v[160:163], v[2:17]
	global_load_dwordx4 v[160:163], v[210:211], off offset:1024
	s_branch .LBB0_332
.Lisel_lasttile:
	s_waitcnt vmcnt(3)
	v_mfma_f32_32x32x16_bf16 v[50:65], v[84:87], v[148:151], 0
	v_mfma_f32_32x32x16_bf16 v[34:49], v[100:103], v[148:151], 0
	v_mfma_f32_32x32x16_bf16 v[18:33], v[116:119], v[148:151], 0
	v_mfma_f32_32x32x16_bf16 v[2:17], v[132:135], v[148:151], 0
	s_waitcnt vmcnt(2)
	v_mfma_f32_32x32x16_bf16 v[50:65], v[88:91], v[152:155], v[50:65]
	v_mfma_f32_32x32x16_bf16 v[34:49], v[104:107], v[152:155], v[34:49]
	v_mfma_f32_32x32x16_bf16 v[18:33], v[120:123], v[152:155], v[18:33]
	v_mfma_f32_32x32x16_bf16 v[2:17], v[136:139], v[152:155], v[2:17]
	s_waitcnt vmcnt(1)
	v_mfma_f32_32x32x16_bf16 v[50:65], v[92:95], v[156:159], v[50:65]
	v_mfma_f32_32x32x16_bf16 v[34:49], v[108:111], v[156:159], v[34:49]
	v_mfma_f32_32x32x16_bf16 v[18:33], v[124:127], v[156:159], v[18:33]
	v_mfma_f32_32x32x16_bf16 v[2:17], v[140:143], v[156:159], v[2:17]
	s_waitcnt vmcnt(0)
	v_mfma_f32_32x32x16_bf16 v[50:65], v[96:99], v[160:163], v[50:65]
	v_mfma_f32_32x32x16_bf16 v[34:49], v[112:115], v[160:163], v[34:49]
	v_mfma_f32_32x32x16_bf16 v[18:33], v[128:131], v[160:163], v[18:33]
	v_mfma_f32_32x32x16_bf16 v[2:17], v[144:147], v[160:163], v[2:17]
	s_branch .LBB0_332
